# grid barrier release path: every workgroup polls the XCD arrival counter TOP >= (gen+1)*nx directly (TOPGEN/XGEN hops dropped), same fences
# speedup vs baseline: 1.0076x; 1.0041x over previous
.LBB0_79:
	v_readlane_b32 s10, v253, 3
	s_lshl_b32 s10, s10, 8
	v_readlane_b32 s12, v253, 1
	v_readlane_b32 s13, v253, 2
	s_add_u32 s10, s12, s10
	s_addc_u32 s11, s13, 0
	v_mov_b32_e32 v1, 0x1000
	v_mov_b32_e32 v3, 1
	global_atomic_add v3, v1, v3, s[10:11] offset:1024 sc0
	v_cvt_f32_u32_e32 v1, v2
	v_sub_u32_e32 v4, 0, v2
	v_rcp_iflag_f32_e32 v1, v1
	s_nop 0
	v_mul_f32_e32 v1, 0x4f7ffffe, v1
	v_cvt_u32_f32_e32 v1, v1
	v_mul_lo_u32 v4, v4, v1
	v_mul_hi_u32 v4, v1, v4
	v_add_u32_e32 v1, v1, v4
	s_waitcnt vmcnt(0)
	v_mul_hi_u32 v1, v3, v1
	v_mul_lo_u32 v4, v1, v2
	v_sub_u32_e32 v4, v3, v4
	v_add_u32_e32 v5, 1, v1
	v_cmp_ge_u32_e32 vcc, v4, v2
	v_add_u32_e32 v3, 1, v3
	s_nop 0
	v_cndmask_b32_e32 v1, v1, v5, vcc
	v_sub_u32_e32 v5, v4, v2
	v_cndmask_b32_e32 v4, v4, v5, vcc
	v_add_u32_e32 v5, 1, v1
	v_cmp_ge_u32_e32 vcc, v4, v2
	s_nop 1
	v_cndmask_b32_e32 v1, v1, v5, vcc
	v_mul_lo_u32 v4, v2, v1
	v_add_u32_e32 v2, v4, v2
	v_cmp_ne_u32_e32 vcc, v3, v2
	s_waitcnt lgkmcnt(0)
	v_add_u32_e32 v4, 1, v1
	v_mul_lo_u32 v4, v4, v0
	v_mov_b32_e32 v2, 0x63000
	s_cbranch_vccnz .Lxb0_wait
	buffer_wbl2 sc1
	s_waitcnt vmcnt(0)
	v_mov_b32_e32 v3, 1
	global_atomic_add v2, v3, s[76:77] offset:1024
.Lxb0_wait:
	s_mov_b32 s12, 0
.Lxb0_spin:
	global_load_dword v3, v2, s[76:77] offset:1024 sc1
	s_waitcnt vmcnt(0)
	v_sub_u32_e32 v3, v3, v4
	v_cmp_gt_i32_e32 vcc, 0, v3
	s_cbranch_vccz .Lxb0_done
	s_sleep 1
	s_add_i32 s12, s12, 1
	s_and_b32 s13, s12, 0xff
	s_cmp_lg_u32 s13, 0
	s_cbranch_scc1 .Lxb0_spin
	v_mov_b32_e32 v0, 0x60000
	global_load_dword v3, v0, s[76:77] offset:512 sc1
	s_waitcnt vmcnt(0)
	v_cmp_ne_u32_e32 vcc, 0, v3
	s_cbranch_vccnz .Lxb0_done
	s_cmp_le_u32 s12, 0x400000
	s_cbranch_scc1 .Lxb0_spin
	v_mov_b32_e32 v3, 1
	global_atomic_add v0, v3, s[76:77] offset:512
.Lxb0_done:
	s_waitcnt vmcnt(0)
	buffer_inv sc1
	s_waitcnt vmcnt(0)

.LBB0_139:
	v_readlane_b32 s6, v253, 3
	s_lshl_b32 s6, s6, 8
	v_readlane_b32 s8, v253, 1
	v_readlane_b32 s9, v253, 2
	s_add_u32 s6, s8, s6
	s_addc_u32 s7, s9, 0
	v_mov_b32_e32 v1, 0x1000
	v_mov_b32_e32 v3, 1
	global_atomic_add v3, v1, v3, s[6:7] offset:1024 sc0
	v_cvt_f32_u32_e32 v1, v2
	v_sub_u32_e32 v4, 0, v2
	v_rcp_iflag_f32_e32 v1, v1
	s_nop 0
	v_mul_f32_e32 v1, 0x4f7ffffe, v1
	v_cvt_u32_f32_e32 v1, v1
	v_mul_lo_u32 v4, v4, v1
	v_mul_hi_u32 v4, v1, v4
	v_add_u32_e32 v1, v1, v4
	s_waitcnt vmcnt(0)
	v_mul_hi_u32 v1, v3, v1
	v_mul_lo_u32 v4, v1, v2
	v_sub_u32_e32 v4, v3, v4
	v_add_u32_e32 v5, 1, v1
	v_cmp_ge_u32_e32 vcc, v4, v2
	v_add_u32_e32 v3, 1, v3
	s_nop 0
	v_cndmask_b32_e32 v1, v1, v5, vcc
	v_sub_u32_e32 v5, v4, v2
	v_cndmask_b32_e32 v4, v4, v5, vcc
	v_add_u32_e32 v5, 1, v1
	v_cmp_ge_u32_e32 vcc, v4, v2
	s_nop 1
	v_cndmask_b32_e32 v1, v1, v5, vcc
	v_mul_lo_u32 v4, v2, v1
	v_add_u32_e32 v2, v4, v2
	v_cmp_ne_u32_e32 vcc, v3, v2
	s_waitcnt lgkmcnt(0)
	v_add_u32_e32 v4, 1, v1
	v_mul_lo_u32 v4, v4, v0
	v_mov_b32_e32 v2, 0x63000
	s_cbranch_vccnz .Lxb1_wait
	buffer_wbl2 sc1
	s_waitcnt vmcnt(0)
	v_mov_b32_e32 v3, 1
	global_atomic_add v2, v3, s[76:77] offset:1024
.Lxb1_wait:
	s_mov_b32 s8, 0
.Lxb1_spin:
	global_load_dword v3, v2, s[76:77] offset:1024 sc1
	s_waitcnt vmcnt(0)
	v_sub_u32_e32 v3, v3, v4
	v_cmp_gt_i32_e32 vcc, 0, v3
	s_cbranch_vccz .Lxb1_done
	s_sleep 1
	s_add_i32 s8, s8, 1
	s_and_b32 s9, s8, 0xff
	s_cmp_lg_u32 s9, 0
	s_cbranch_scc1 .Lxb1_spin
	v_mov_b32_e32 v0, 0x60000
	global_load_dword v3, v0, s[76:77] offset:512 sc1
	s_waitcnt vmcnt(0)
	v_cmp_ne_u32_e32 vcc, 0, v3
	s_cbranch_vccnz .Lxb1_done
	s_cmp_le_u32 s8, 0x400000
	s_cbranch_scc1 .Lxb1_spin
	v_mov_b32_e32 v3, 1
	global_atomic_add v0, v3, s[76:77] offset:512

.LBB0_1017:
	v_readlane_b32 s4, v253, 3
	s_lshl_b32 s4, s4, 8
	v_readlane_b32 s6, v253, 1
	v_readlane_b32 s7, v253, 2
	s_add_u32 s4, s6, s4
	s_addc_u32 s5, s7, 0
	v_mov_b32_e32 v1, 0x1000
	v_mov_b32_e32 v3, 1
	global_atomic_add v3, v1, v3, s[4:5] offset:1024 sc0
	v_cvt_f32_u32_e32 v1, v2
	v_sub_u32_e32 v4, 0, v2
	v_rcp_iflag_f32_e32 v1, v1
	s_nop 0
	v_mul_f32_e32 v1, 0x4f7ffffe, v1
	v_cvt_u32_f32_e32 v1, v1
	v_mul_lo_u32 v4, v4, v1
	v_mul_hi_u32 v4, v1, v4
	v_add_u32_e32 v1, v1, v4
	s_waitcnt vmcnt(0)
	v_mul_hi_u32 v1, v3, v1
	v_mul_lo_u32 v4, v1, v2
	v_sub_u32_e32 v4, v3, v4
	v_add_u32_e32 v5, 1, v1
	v_cmp_ge_u32_e32 vcc, v4, v2
	v_add_u32_e32 v3, 1, v3
	s_nop 0
	v_cndmask_b32_e32 v1, v1, v5, vcc
	v_sub_u32_e32 v5, v4, v2
	v_cndmask_b32_e32 v4, v4, v5, vcc
	v_add_u32_e32 v5, 1, v1
	v_cmp_ge_u32_e32 vcc, v4, v2
	s_nop 1
	v_cndmask_b32_e32 v1, v1, v5, vcc
	v_mul_lo_u32 v4, v2, v1
	v_add_u32_e32 v2, v4, v2
	v_cmp_ne_u32_e32 vcc, v3, v2
	s_waitcnt lgkmcnt(0)
	v_add_u32_e32 v4, 1, v1
	v_mul_lo_u32 v4, v4, v0
	v_mov_b32_e32 v2, 0x63000
	s_cbranch_vccnz .Lxb3_wait
	buffer_wbl2 sc1
	s_waitcnt vmcnt(0)
	v_mov_b32_e32 v3, 1
	global_atomic_add v2, v3, s[76:77] offset:1024
.Lxb3_wait:
	s_mov_b32 s6, 0
.Lxb3_spin:
	global_load_dword v3, v2, s[76:77] offset:1024 sc1
	s_waitcnt vmcnt(0)
	v_sub_u32_e32 v3, v3, v4
	v_cmp_gt_i32_e32 vcc, 0, v3
	s_cbranch_vccz .Lxb3_done
	s_sleep 1
	s_add_i32 s6, s6, 1
	s_and_b32 s7, s6, 0xff
	s_cmp_lg_u32 s7, 0
	s_cbranch_scc1 .Lxb3_spin
	v_mov_b32_e32 v0, 0x60000
	global_load_dword v3, v0, s[76:77] offset:512 sc1
	s_waitcnt vmcnt(0)
	v_cmp_ne_u32_e32 vcc, 0, v3
	s_cbranch_vccnz .Lxb3_done
	s_cmp_le_u32 s6, 0x400000
	s_cbranch_scc1 .Lxb3_spin
	v_mov_b32_e32 v3, 1
	global_atomic_add v0, v3, s[76:77] offset:512
